# grid-barrier poll loops: s_sleep 1 replaced by s_nop (exit-latency trim) on top of v031
# speedup vs baseline: 1.0008x; 1.0008x over previous
; __global__ void __launch_bounds__(512, 2) fwd_megakernel(Params p) {
;     ...
;   grid.sync();
.LBB0_135:
	s_nop 0
	global_load_dword v2, v0, s[6:7] offset:32 sc1
	s_waitcnt vmcnt(0)
	v_and_b32_e32 v2, 0xffff0000, v2
	v_cmp_ne_u32_e32 vcc, v2, v1
	s_or_b64 s[8:9], vcc, s[8:9]
	s_andn2_b64 exec, exec, s[8:9]
	s_cbranch_execnz .LBB0_135

; __device__ __forceinline__ unsigned xb_ld(unsigned* p)              { return __hip_atomic_load(p, __ATOMIC_RELAXED, __HIP_MEMORY_SCOPE_AGENT); }
; __device__ __forceinline__ void xcd_barrier_complete(unsigned* bar, unsigned x, unsigned& nloc, unsigned& nx) {
;   const unsigned G = gridDim.x * gridDim.y * gridDim.z;
;   unsigned sum, cnt, mine, sp = 0u;
;   for (;;) {
;     sum = 0u; cnt = 0u; mine = 0u;
; #pragma unroll
;     for (unsigned j = 0; j < 16; ++j) { const unsigned c = xb_ld(&bar[XB_XCNT(j)]); sum += c; cnt += (c > 0u) ? 1u : 0u; mine = (j == x) ? c : mine; }
;     if (sum == G) break;
;     __builtin_amdgcn_s_sleep(1);
;     if ((++sp & 255u) == 0u) { if (xb_ld(&bar[XB_TMO])) break; if (sp > XB_SPIN_CAP) { atomicAdd(&bar[XB_TMO], 1u); break; } }
;   }
;   nloc = mine > 0u ? mine : 1u; nx = cnt > 0u ? cnt : 1u;
; }
.LBB0_144:
	global_load_dword v15, v16, s[8:9] sc1
	global_load_dword v0, v16, s[10:11] sc1
	global_load_dword v1, v16, s[12:13] sc1
	global_load_dword v2, v16, s[14:15] sc1
	global_load_dword v3, v16, s[16:17] sc1
	global_load_dword v4, v16, s[18:19] sc1
	global_load_dword v5, v16, s[20:21] sc1
	global_load_dword v6, v16, s[22:23] sc1
	global_load_dword v7, v16, s[24:25] sc1
	global_load_dword v8, v16, s[26:27] sc1
	global_load_dword v9, v16, s[28:29] sc1
	global_load_dword v10, v16, s[30:31] sc1
	global_load_dword v11, v16, s[34:35] sc1
	global_load_dword v12, v16, s[36:37] sc1
	global_load_dword v13, v16, s[38:39] sc1
	global_load_dword v14, v16, s[40:41] sc1
	s_mov_b64 s[42:43], -1
	s_mov_b64 s[44:45], -1
	s_waitcnt vmcnt(14)
	v_add_u32_e32 v17, v0, v15
	s_waitcnt vmcnt(13)
	v_add_u32_e32 v17, v17, v1
	s_waitcnt vmcnt(12)
	v_add_u32_e32 v17, v17, v2
	s_waitcnt vmcnt(11)
	v_add_u32_e32 v17, v17, v3
	s_waitcnt vmcnt(10)
	v_add_u32_e32 v17, v17, v4
	s_waitcnt vmcnt(9)
	v_add_u32_e32 v17, v17, v5
	s_waitcnt vmcnt(8)
	v_add_u32_e32 v17, v17, v6
	s_waitcnt vmcnt(7)
	v_add_u32_e32 v17, v17, v7
	s_waitcnt vmcnt(6)
	v_add_u32_e32 v17, v17, v8
	s_waitcnt vmcnt(5)
	v_add_u32_e32 v17, v17, v9
	s_waitcnt vmcnt(4)
	v_add_u32_e32 v17, v17, v10
	s_waitcnt vmcnt(3)
	v_add_u32_e32 v17, v17, v11
	s_waitcnt vmcnt(2)
	v_add_u32_e32 v17, v17, v12
	s_waitcnt vmcnt(1)
	v_add_u32_e32 v17, v17, v13
	s_waitcnt vmcnt(0)
	v_add_u32_e32 v17, v17, v14
	v_cmp_eq_u32_e32 vcc, s0, v17
	s_cbranch_vccnz .LBB0_143
	s_and_b32 s2, s1, 0xff
	s_cmp_eq_u32 s2, 0
	s_mov_b64 s[46:47], -1
	s_nop 0
	s_cbranch_scc0 .LBB0_148
	global_load_dword v17, v16, s[6:7] sc1
	s_waitcnt vmcnt(0)
	v_cmp_eq_u32_e32 vcc, 0, v17
	s_cbranch_vccnz .LBB0_150
	s_mov_b64 s[46:47], 0

; __device__ __forceinline__ unsigned xb_ld(unsigned* p)              { return __hip_atomic_load(p, __ATOMIC_RELAXED, __HIP_MEMORY_SCOPE_AGENT); }
; __device__ __forceinline__ unsigned xb_add(unsigned* p, unsigned v) { return __hip_atomic_fetch_add(p, v, __ATOMIC_RELAXED, __HIP_MEMORY_SCOPE_AGENT); }
; #define XB_SPIN(cond, bar) do { unsigned _sp = 0; while (cond) { __builtin_amdgcn_s_sleep(1); \
;     if ((++_sp & 255u) == 0u) { if (xb_ld(&(bar)[XB_TMO])) break; if (_sp > XB_SPIN_CAP) { atomicAdd(&(bar)[XB_TMO], 1u); break; } } } } while (0)
; __device__ __forceinline__ void xcd_barrier(const XcdBarrier& b) {
;     ...
;     const unsigned old = xb_add(&bar[XB_XSUB(b.x)], 1u);
;     const unsigned gen = old / nloc;
;     if (old + 1u == (gen + 1u) * nloc) {
;       __builtin_amdgcn_fence(__ATOMIC_RELEASE, "agent");
;       asm volatile("s_waitcnt vmcnt(0)" ::: "memory");
;       const unsigned og = xb_add(&bar[XB_TOP], 1u);
;       const unsigned tg = og / nx;
;       if (og + 1u == (tg + 1u) * nx) xb_add(&bar[XB_TOPGEN], 1u);
;       else XB_SPIN(xb_ld(&bar[XB_TOPGEN]) == tg, bar);
;       __builtin_amdgcn_fence(__ATOMIC_ACQUIRE, "agent");
;       xb_add(&bar[XB_XGEN(b.x)], 1u);
;       asm volatile("s_waitcnt vmcnt(0)" ::: "memory");
;     } else {
;       XB_SPIN(xb_ld(&bar[XB_XGEN(b.x)]) == gen, bar);
;       __builtin_amdgcn_fence(__ATOMIC_ACQUIRE, "agent");
;       asm volatile("s_waitcnt vmcnt(0)" ::: "memory");
;     }
.LBB0_162:
	s_and_b32 s1, s0, 0xff
	s_mov_b64 s[20:21], -1
	s_cmp_lg_u32 s1, 0
	s_mov_b64 s[24:25], -1
	s_nop 0
	s_cbranch_scc1 .LBB0_165
	global_load_dword v2, v0, s[12:13] sc1
	s_waitcnt vmcnt(0)
	v_cmp_eq_u32_e32 vcc, 0, v2
	s_cbranch_vccnz .LBB0_167
	s_mov_b64 s[24:25], 0
	s_mov_b64 s[22:23], -1

; __device__ __forceinline__ unsigned xb_ld(unsigned* p)              { return __hip_atomic_load(p, __ATOMIC_RELAXED, __HIP_MEMORY_SCOPE_AGENT); }
; __device__ __forceinline__ unsigned xb_add(unsigned* p, unsigned v) { return __hip_atomic_fetch_add(p, v, __ATOMIC_RELAXED, __HIP_MEMORY_SCOPE_AGENT); }
; #define XB_SPIN(cond, bar) do { unsigned _sp = 0; while (cond) { __builtin_amdgcn_s_sleep(1); \
;     if ((++_sp & 255u) == 0u) { if (xb_ld(&(bar)[XB_TMO])) break; if (_sp > XB_SPIN_CAP) { atomicAdd(&(bar)[XB_TMO], 1u); break; } } } } while (0)
; __device__ __forceinline__ void xcd_barrier(const XcdBarrier& b) {
;     ...
;     const unsigned old = xb_add(&bar[XB_XSUB(b.x)], 1u);
;     const unsigned gen = old / nloc;
;     if (old + 1u == (gen + 1u) * nloc) {
;       __builtin_amdgcn_fence(__ATOMIC_RELEASE, "agent");
;       asm volatile("s_waitcnt vmcnt(0)" ::: "memory");
;       const unsigned og = xb_add(&bar[XB_TOP], 1u);
;       const unsigned tg = og / nx;
;       if (og + 1u == (tg + 1u) * nx) xb_add(&bar[XB_TOPGEN], 1u);
;       else XB_SPIN(xb_ld(&bar[XB_TOPGEN]) == tg, bar);
;       __builtin_amdgcn_fence(__ATOMIC_ACQUIRE, "agent");
;       xb_add(&bar[XB_XGEN(b.x)], 1u);
;       asm volatile("s_waitcnt vmcnt(0)" ::: "memory");
;     } else {
;       XB_SPIN(xb_ld(&bar[XB_XGEN(b.x)]) == gen, bar);
;       __builtin_amdgcn_fence(__ATOMIC_ACQUIRE, "agent");
;       asm volatile("s_waitcnt vmcnt(0)" ::: "memory");
;     }
.LBB0_179:
	s_and_b32 s1, s0, 0xff
	s_cmp_lg_u32 s1, 0
	s_mov_b64 s[22:23], -1
	s_nop 0
	s_cbranch_scc1 .LBB0_182
	global_load_dword v1, v0, s[12:13] sc1
	s_waitcnt vmcnt(0)
	v_cmp_eq_u32_e32 vcc, 0, v1
	s_cbranch_vccnz .LBB0_184
	s_mov_b64 s[22:23], 0
	s_mov_b64 s[20:21], -1

; __device__ __forceinline__ unsigned xb_ld(unsigned* p)              { return __hip_atomic_load(p, __ATOMIC_RELAXED, __HIP_MEMORY_SCOPE_AGENT); }
; __device__ __forceinline__ void xcd_barrier_complete(unsigned* bar, unsigned x, unsigned& nloc, unsigned& nx) {
;   const unsigned G = gridDim.x * gridDim.y * gridDim.z;
;   unsigned sum, cnt, mine, sp = 0u;
;   for (;;) {
;     sum = 0u; cnt = 0u; mine = 0u;
; #pragma unroll
;     for (unsigned j = 0; j < 16; ++j) { const unsigned c = xb_ld(&bar[XB_XCNT(j)]); sum += c; cnt += (c > 0u) ? 1u : 0u; mine = (j == x) ? c : mine; }
;     if (sum == G) break;
;     __builtin_amdgcn_s_sleep(1);
;     if ((++sp & 255u) == 0u) { if (xb_ld(&bar[XB_TMO])) break; if (sp > XB_SPIN_CAP) { atomicAdd(&bar[XB_TMO], 1u); break; } }
;   }
;   nloc = mine > 0u ? mine : 1u; nx = cnt > 0u ? cnt : 1u;
; }
.LBB0_552:
	global_load_dword v15, v16, s[8:9] sc1
	s_waitcnt lgkmcnt(0)
	global_load_dword v0, v16, s[10:11] sc1
	global_load_dword v1, v16, s[12:13] sc1
	global_load_dword v2, v16, s[14:15] sc1
	global_load_dword v3, v16, s[16:17] sc1
	global_load_dword v4, v16, s[18:19] sc1
	global_load_dword v5, v16, s[20:21] sc1
	global_load_dword v6, v16, s[22:23] sc1
	global_load_dword v7, v16, s[24:25] sc1
	global_load_dword v8, v16, s[26:27] sc1
	global_load_dword v9, v16, s[28:29] sc1
	global_load_dword v10, v16, s[30:31] sc1
	global_load_dword v11, v16, s[34:35] sc1
	global_load_dword v12, v16, s[36:37] sc1
	global_load_dword v13, v16, s[38:39] sc1
	global_load_dword v14, v16, s[40:41] sc1
	s_mov_b64 s[42:43], -1
	s_mov_b64 s[44:45], -1
	s_waitcnt vmcnt(14)
	v_add_u32_e32 v17, v0, v15
	s_waitcnt vmcnt(13)
	v_add_u32_e32 v17, v17, v1
	s_waitcnt vmcnt(12)
	v_add_u32_e32 v17, v17, v2
	s_waitcnt vmcnt(11)
	v_add_u32_e32 v17, v17, v3
	s_waitcnt vmcnt(10)
	v_add_u32_e32 v17, v17, v4
	s_waitcnt vmcnt(9)
	v_add_u32_e32 v17, v17, v5
	s_waitcnt vmcnt(8)
	v_add_u32_e32 v17, v17, v6
	s_waitcnt vmcnt(7)
	v_add_u32_e32 v17, v17, v7
	s_waitcnt vmcnt(6)
	v_add_u32_e32 v17, v17, v8
	s_waitcnt vmcnt(5)
	v_add_u32_e32 v17, v17, v9
	s_waitcnt vmcnt(4)
	v_add_u32_e32 v17, v17, v10
	s_waitcnt vmcnt(3)
	v_add_u32_e32 v17, v17, v11
	s_waitcnt vmcnt(2)
	v_add_u32_e32 v17, v17, v12
	s_waitcnt vmcnt(1)
	v_add_u32_e32 v17, v17, v13
	s_waitcnt vmcnt(0)
	v_add_u32_e32 v17, v17, v14
	v_cmp_eq_u32_e32 vcc, s0, v17
	s_cbranch_vccnz .LBB0_551
	s_and_b32 s2, s1, 0xff
	s_cmp_eq_u32 s2, 0
	s_mov_b64 s[46:47], -1
	s_nop 0
	s_cbranch_scc0 .LBB0_556
	global_load_dword v17, v16, s[6:7] sc1
	s_waitcnt vmcnt(0)
	v_cmp_eq_u32_e32 vcc, 0, v17
	s_cbranch_vccnz .LBB0_558
	s_mov_b64 s[46:47], 0

; __device__ __forceinline__ unsigned xb_ld(unsigned* p)              { return __hip_atomic_load(p, __ATOMIC_RELAXED, __HIP_MEMORY_SCOPE_AGENT); }
; __device__ __forceinline__ void xcd_barrier_complete(unsigned* bar, unsigned x, unsigned& nloc, unsigned& nx) {
;   const unsigned G = gridDim.x * gridDim.y * gridDim.z;
;   unsigned sum, cnt, mine, sp = 0u;
;   for (;;) {
;     sum = 0u; cnt = 0u; mine = 0u;
; #pragma unroll
;     for (unsigned j = 0; j < 16; ++j) { const unsigned c = xb_ld(&bar[XB_XCNT(j)]); sum += c; cnt += (c > 0u) ? 1u : 0u; mine = (j == x) ? c : mine; }
;     if (sum == G) break;
;     __builtin_amdgcn_s_sleep(1);
;     if ((++sp & 255u) == 0u) { if (xb_ld(&bar[XB_TMO])) break; if (sp > XB_SPIN_CAP) { atomicAdd(&bar[XB_TMO], 1u); break; } }
;   }
;   nloc = mine > 0u ? mine : 1u; nx = cnt > 0u ? cnt : 1u;
; }
.LBB0_679:
	global_load_dword v15, v16, s[8:9] sc1
	s_waitcnt lgkmcnt(0)
	global_load_dword v0, v16, s[10:11] sc1
	global_load_dword v1, v16, s[12:13] sc1
	global_load_dword v2, v16, s[16:17] sc1
	global_load_dword v3, v16, s[18:19] sc1
	global_load_dword v4, v16, s[20:21] sc1
	global_load_dword v5, v16, s[22:23] sc1
	global_load_dword v6, v16, s[24:25] sc1
	global_load_dword v7, v16, s[26:27] sc1
	global_load_dword v8, v16, s[28:29] sc1
	global_load_dword v9, v16, s[30:31] sc1
	global_load_dword v10, v16, s[34:35] sc1
	global_load_dword v11, v16, s[36:37] sc1
	global_load_dword v12, v16, s[38:39] sc1
	global_load_dword v13, v16, s[40:41] sc1
	global_load_dword v14, v16, s[42:43] sc1
	s_mov_b64 s[44:45], -1
	s_mov_b64 s[46:47], -1
	s_waitcnt vmcnt(14)
	v_add_u32_e32 v17, v0, v15
	s_waitcnt vmcnt(13)
	v_add_u32_e32 v17, v17, v1
	s_waitcnt vmcnt(12)
	v_add_u32_e32 v17, v17, v2
	s_waitcnt vmcnt(11)
	v_add_u32_e32 v17, v17, v3
	s_waitcnt vmcnt(10)
	v_add_u32_e32 v17, v17, v4
	s_waitcnt vmcnt(9)
	v_add_u32_e32 v17, v17, v5
	s_waitcnt vmcnt(8)
	v_add_u32_e32 v17, v17, v6
	s_waitcnt vmcnt(7)
	v_add_u32_e32 v17, v17, v7
	s_waitcnt vmcnt(6)
	v_add_u32_e32 v17, v17, v8
	s_waitcnt vmcnt(5)
	v_add_u32_e32 v17, v17, v9
	s_waitcnt vmcnt(4)
	v_add_u32_e32 v17, v17, v10
	s_waitcnt vmcnt(3)
	v_add_u32_e32 v17, v17, v11
	s_waitcnt vmcnt(2)
	v_add_u32_e32 v17, v17, v12
	s_waitcnt vmcnt(1)
	v_add_u32_e32 v17, v17, v13
	s_waitcnt vmcnt(0)
	v_add_u32_e32 v17, v17, v14
	v_cmp_eq_u32_e32 vcc, s0, v17
	s_cbranch_vccnz .LBB0_678
	s_and_b32 s2, s1, 0xff
	s_cmp_eq_u32 s2, 0
	s_mov_b64 s[48:49], -1
	s_nop 0
	s_cbranch_scc0 .LBB0_683
	global_load_dword v17, v16, s[6:7] sc1
	s_waitcnt vmcnt(0)
	v_cmp_eq_u32_e32 vcc, 0, v17
	s_cbranch_vccnz .LBB0_685
	s_mov_b64 s[48:49], 0

; __device__ __forceinline__ unsigned xb_ld(unsigned* p)              { return __hip_atomic_load(p, __ATOMIC_RELAXED, __HIP_MEMORY_SCOPE_AGENT); }
; __device__ __forceinline__ unsigned xb_add(unsigned* p, unsigned v) { return __hip_atomic_fetch_add(p, v, __ATOMIC_RELAXED, __HIP_MEMORY_SCOPE_AGENT); }
; #define XB_SPIN(cond, bar) do { unsigned _sp = 0; while (cond) { __builtin_amdgcn_s_sleep(1); \
;     if ((++_sp & 255u) == 0u) { if (xb_ld(&(bar)[XB_TMO])) break; if (_sp > XB_SPIN_CAP) { atomicAdd(&(bar)[XB_TMO], 1u); break; } } } } while (0)
; __device__ __forceinline__ void xcd_barrier(const XcdBarrier& b) {
;     ...
;     const unsigned old = xb_add(&bar[XB_XSUB(b.x)], 1u);
;     const unsigned gen = old / nloc;
;     if (old + 1u == (gen + 1u) * nloc) {
;       __builtin_amdgcn_fence(__ATOMIC_RELEASE, "agent");
;       asm volatile("s_waitcnt vmcnt(0)" ::: "memory");
;       const unsigned og = xb_add(&bar[XB_TOP], 1u);
;       const unsigned tg = og / nx;
;       if (og + 1u == (tg + 1u) * nx) xb_add(&bar[XB_TOPGEN], 1u);
;       else XB_SPIN(xb_ld(&bar[XB_TOPGEN]) == tg, bar);
;       __builtin_amdgcn_fence(__ATOMIC_ACQUIRE, "agent");
;       xb_add(&bar[XB_XGEN(b.x)], 1u);
;       asm volatile("s_waitcnt vmcnt(0)" ::: "memory");
;     } else {
;       XB_SPIN(xb_ld(&bar[XB_XGEN(b.x)]) == gen, bar);
;       __builtin_amdgcn_fence(__ATOMIC_ACQUIRE, "agent");
;       asm volatile("s_waitcnt vmcnt(0)" ::: "memory");
;     }
.LBB0_697:
	s_and_b32 s1, s0, 0xff
	s_mov_b64 s[22:23], -1
	s_cmp_lg_u32 s1, 0
	s_mov_b64 s[26:27], -1
	s_nop 0
	s_cbranch_scc1 .LBB0_700
	global_load_dword v2, v0, s[12:13] sc1
	s_waitcnt vmcnt(0)
	v_cmp_eq_u32_e32 vcc, 0, v2
	s_cbranch_vccnz .LBB0_702
	s_mov_b64 s[26:27], 0
	s_mov_b64 s[24:25], -1

; __device__ __forceinline__ unsigned xb_ld(unsigned* p)              { return __hip_atomic_load(p, __ATOMIC_RELAXED, __HIP_MEMORY_SCOPE_AGENT); }
; __device__ __forceinline__ unsigned xb_add(unsigned* p, unsigned v) { return __hip_atomic_fetch_add(p, v, __ATOMIC_RELAXED, __HIP_MEMORY_SCOPE_AGENT); }
; #define XB_SPIN(cond, bar) do { unsigned _sp = 0; while (cond) { __builtin_amdgcn_s_sleep(1); \
;     if ((++_sp & 255u) == 0u) { if (xb_ld(&(bar)[XB_TMO])) break; if (_sp > XB_SPIN_CAP) { atomicAdd(&(bar)[XB_TMO], 1u); break; } } } } while (0)
; __device__ __forceinline__ void xcd_barrier(const XcdBarrier& b) {
;     ...
;     const unsigned old = xb_add(&bar[XB_XSUB(b.x)], 1u);
;     const unsigned gen = old / nloc;
;     if (old + 1u == (gen + 1u) * nloc) {
;       __builtin_amdgcn_fence(__ATOMIC_RELEASE, "agent");
;       asm volatile("s_waitcnt vmcnt(0)" ::: "memory");
;       const unsigned og = xb_add(&bar[XB_TOP], 1u);
;       const unsigned tg = og / nx;
;       if (og + 1u == (tg + 1u) * nx) xb_add(&bar[XB_TOPGEN], 1u);
;       else XB_SPIN(xb_ld(&bar[XB_TOPGEN]) == tg, bar);
;       __builtin_amdgcn_fence(__ATOMIC_ACQUIRE, "agent");
;       xb_add(&bar[XB_XGEN(b.x)], 1u);
;       asm volatile("s_waitcnt vmcnt(0)" ::: "memory");
;     } else {
;       XB_SPIN(xb_ld(&bar[XB_XGEN(b.x)]) == gen, bar);
;       __builtin_amdgcn_fence(__ATOMIC_ACQUIRE, "agent");
;       asm volatile("s_waitcnt vmcnt(0)" ::: "memory");
;     }
.LBB0_714:
	s_and_b32 s1, s0, 0xff
	s_cmp_lg_u32 s1, 0
	s_mov_b64 s[24:25], -1
	s_nop 0
	s_cbranch_scc1 .LBB0_717
	global_load_dword v1, v0, s[12:13] sc1
	s_waitcnt vmcnt(0)
	v_cmp_eq_u32_e32 vcc, 0, v1
	s_cbranch_vccnz .LBB0_719
	s_mov_b64 s[24:25], 0
	s_mov_b64 s[22:23], -1

; __device__ __forceinline__ unsigned xb_ld(unsigned* p)              { return __hip_atomic_load(p, __ATOMIC_RELAXED, __HIP_MEMORY_SCOPE_AGENT); }
; __device__ __forceinline__ void xcd_barrier_complete(unsigned* bar, unsigned x, unsigned& nloc, unsigned& nx) {
;   const unsigned G = gridDim.x * gridDim.y * gridDim.z;
;   unsigned sum, cnt, mine, sp = 0u;
;   for (;;) {
;     sum = 0u; cnt = 0u; mine = 0u;
; #pragma unroll
;     for (unsigned j = 0; j < 16; ++j) { const unsigned c = xb_ld(&bar[XB_XCNT(j)]); sum += c; cnt += (c > 0u) ? 1u : 0u; mine = (j == x) ? c : mine; }
;     if (sum == G) break;
;     __builtin_amdgcn_s_sleep(1);
;     if ((++sp & 255u) == 0u) { if (xb_ld(&bar[XB_TMO])) break; if (sp > XB_SPIN_CAP) { atomicAdd(&bar[XB_TMO], 1u); break; } }
;   }
;   nloc = mine > 0u ? mine : 1u; nx = cnt > 0u ? cnt : 1u;
; }
.LBB0_775:
	global_load_dword v15, v16, s[16:17] sc1
	s_waitcnt lgkmcnt(0)
	global_load_dword v0, v16, s[18:19] sc1
	global_load_dword v1, v16, s[20:21] sc1
	global_load_dword v2, v16, s[22:23] sc1
	global_load_dword v3, v16, s[24:25] sc1
	global_load_dword v4, v16, s[26:27] sc1
	global_load_dword v5, v16, s[30:31] sc1
	global_load_dword v6, v16, s[34:35] sc1
	global_load_dword v7, v16, s[36:37] sc1
	global_load_dword v8, v16, s[38:39] sc1
	global_load_dword v9, v16, s[40:41] sc1
	global_load_dword v10, v16, s[42:43] sc1
	global_load_dword v11, v16, s[44:45] sc1
	global_load_dword v12, v16, s[46:47] sc1
	global_load_dword v13, v16, s[48:49] sc1
	global_load_dword v14, v16, s[50:51] sc1
	s_mov_b64 s[52:53], -1
	s_mov_b64 s[54:55], -1
	s_waitcnt vmcnt(14)
	v_add_u32_e32 v17, v0, v15
	s_waitcnt vmcnt(13)
	v_add_u32_e32 v17, v17, v1
	s_waitcnt vmcnt(12)
	v_add_u32_e32 v17, v17, v2
	s_waitcnt vmcnt(11)
	v_add_u32_e32 v17, v17, v3
	s_waitcnt vmcnt(10)
	v_add_u32_e32 v17, v17, v4
	s_waitcnt vmcnt(9)
	v_add_u32_e32 v17, v17, v5
	s_waitcnt vmcnt(8)
	v_add_u32_e32 v17, v17, v6
	s_waitcnt vmcnt(7)
	v_add_u32_e32 v17, v17, v7
	s_waitcnt vmcnt(6)
	v_add_u32_e32 v17, v17, v8
	s_waitcnt vmcnt(5)
	v_add_u32_e32 v17, v17, v9
	s_waitcnt vmcnt(4)
	v_add_u32_e32 v17, v17, v10
	s_waitcnt vmcnt(3)
	v_add_u32_e32 v17, v17, v11
	s_waitcnt vmcnt(2)
	v_add_u32_e32 v17, v17, v12
	s_waitcnt vmcnt(1)
	v_add_u32_e32 v17, v17, v13
	s_waitcnt vmcnt(0)
	v_add_u32_e32 v17, v17, v14
	v_cmp_eq_u32_e32 vcc, s0, v17
	s_cbranch_vccnz .LBB0_774
	s_and_b32 s2, s1, 0xff
	s_cmp_eq_u32 s2, 0
	s_mov_b64 s[56:57], -1
	s_nop 0
	s_cbranch_scc0 .LBB0_779
	global_load_dword v17, v16, s[6:7] sc1
	s_waitcnt vmcnt(0)
	v_cmp_eq_u32_e32 vcc, 0, v17
	s_cbranch_vccnz .LBB0_781
	s_mov_b64 s[56:57], 0

; __device__ __forceinline__ unsigned xb_ld(unsigned* p)              { return __hip_atomic_load(p, __ATOMIC_RELAXED, __HIP_MEMORY_SCOPE_AGENT); }
; __device__ __forceinline__ unsigned xb_add(unsigned* p, unsigned v) { return __hip_atomic_fetch_add(p, v, __ATOMIC_RELAXED, __HIP_MEMORY_SCOPE_AGENT); }
; #define XB_SPIN(cond, bar) do { unsigned _sp = 0; while (cond) { __builtin_amdgcn_s_sleep(1); \
;     if ((++_sp & 255u) == 0u) { if (xb_ld(&(bar)[XB_TMO])) break; if (_sp > XB_SPIN_CAP) { atomicAdd(&(bar)[XB_TMO], 1u); break; } } } } while (0)
; __device__ __forceinline__ void xcd_barrier(const XcdBarrier& b) {
;     ...
;     const unsigned old = xb_add(&bar[XB_XSUB(b.x)], 1u);
;     const unsigned gen = old / nloc;
;     if (old + 1u == (gen + 1u) * nloc) {
;       __builtin_amdgcn_fence(__ATOMIC_RELEASE, "agent");
;       asm volatile("s_waitcnt vmcnt(0)" ::: "memory");
;       const unsigned og = xb_add(&bar[XB_TOP], 1u);
;       const unsigned tg = og / nx;
;       if (og + 1u == (tg + 1u) * nx) xb_add(&bar[XB_TOPGEN], 1u);
;       else XB_SPIN(xb_ld(&bar[XB_TOPGEN]) == tg, bar);
;       __builtin_amdgcn_fence(__ATOMIC_ACQUIRE, "agent");
;       xb_add(&bar[XB_XGEN(b.x)], 1u);
;       asm volatile("s_waitcnt vmcnt(0)" ::: "memory");
;     } else {
;       XB_SPIN(xb_ld(&bar[XB_XGEN(b.x)]) == gen, bar);
;       __builtin_amdgcn_fence(__ATOMIC_ACQUIRE, "agent");
;       asm volatile("s_waitcnt vmcnt(0)" ::: "memory");
;     }
.LBB0_793:
	s_and_b32 s1, s0, 0xff
	s_mov_b64 s[30:31], -1
	s_cmp_lg_u32 s1, 0
	s_mov_b64 s[36:37], -1
	s_nop 0
	s_cbranch_scc1 .LBB0_796
	global_load_dword v2, v0, s[20:21] sc1
	s_waitcnt vmcnt(0)
	v_cmp_eq_u32_e32 vcc, 0, v2
	s_cbranch_vccnz .LBB0_798
	s_mov_b64 s[36:37], 0
	s_mov_b64 s[34:35], -1

; __device__ __forceinline__ unsigned xb_ld(unsigned* p)              { return __hip_atomic_load(p, __ATOMIC_RELAXED, __HIP_MEMORY_SCOPE_AGENT); }
; __device__ __forceinline__ unsigned xb_add(unsigned* p, unsigned v) { return __hip_atomic_fetch_add(p, v, __ATOMIC_RELAXED, __HIP_MEMORY_SCOPE_AGENT); }
; #define XB_SPIN(cond, bar) do { unsigned _sp = 0; while (cond) { __builtin_amdgcn_s_sleep(1); \
;     if ((++_sp & 255u) == 0u) { if (xb_ld(&(bar)[XB_TMO])) break; if (_sp > XB_SPIN_CAP) { atomicAdd(&(bar)[XB_TMO], 1u); break; } } } } while (0)
; __device__ __forceinline__ void xcd_barrier(const XcdBarrier& b) {
;     ...
;     const unsigned old = xb_add(&bar[XB_XSUB(b.x)], 1u);
;     const unsigned gen = old / nloc;
;     if (old + 1u == (gen + 1u) * nloc) {
;       __builtin_amdgcn_fence(__ATOMIC_RELEASE, "agent");
;       asm volatile("s_waitcnt vmcnt(0)" ::: "memory");
;       const unsigned og = xb_add(&bar[XB_TOP], 1u);
;       const unsigned tg = og / nx;
;       if (og + 1u == (tg + 1u) * nx) xb_add(&bar[XB_TOPGEN], 1u);
;       else XB_SPIN(xb_ld(&bar[XB_TOPGEN]) == tg, bar);
;       __builtin_amdgcn_fence(__ATOMIC_ACQUIRE, "agent");
;       xb_add(&bar[XB_XGEN(b.x)], 1u);
;       asm volatile("s_waitcnt vmcnt(0)" ::: "memory");
;     } else {
;       XB_SPIN(xb_ld(&bar[XB_XGEN(b.x)]) == gen, bar);
;       __builtin_amdgcn_fence(__ATOMIC_ACQUIRE, "agent");
;       asm volatile("s_waitcnt vmcnt(0)" ::: "memory");
;     }
.LBB0_810:
	s_and_b32 s1, s0, 0xff
	s_cmp_lg_u32 s1, 0
	s_mov_b64 s[34:35], -1
	s_nop 0
	s_cbranch_scc1 .LBB0_813
	global_load_dword v1, v0, s[20:21] sc1
	s_waitcnt vmcnt(0)
	v_cmp_eq_u32_e32 vcc, 0, v1
	s_cbranch_vccnz .LBB0_815
	s_mov_b64 s[34:35], 0
	s_mov_b64 s[30:31], -1

; __device__ __forceinline__ unsigned xb_ld(unsigned* p)              { return __hip_atomic_load(p, __ATOMIC_RELAXED, __HIP_MEMORY_SCOPE_AGENT); }
; __device__ __forceinline__ void xcd_barrier_complete(unsigned* bar, unsigned x, unsigned& nloc, unsigned& nx) {
;   const unsigned G = gridDim.x * gridDim.y * gridDim.z;
;   unsigned sum, cnt, mine, sp = 0u;
;   for (;;) {
;     sum = 0u; cnt = 0u; mine = 0u;
; #pragma unroll
;     for (unsigned j = 0; j < 16; ++j) { const unsigned c = xb_ld(&bar[XB_XCNT(j)]); sum += c; cnt += (c > 0u) ? 1u : 0u; mine = (j == x) ? c : mine; }
;     if (sum == G) break;
;     __builtin_amdgcn_s_sleep(1);
;     if ((++sp & 255u) == 0u) { if (xb_ld(&bar[XB_TMO])) break; if (sp > XB_SPIN_CAP) { atomicAdd(&bar[XB_TMO], 1u); break; } }
;   }
;   nloc = mine > 0u ? mine : 1u; nx = cnt > 0u ? cnt : 1u;
; }
.LBB0_1012:
	global_load_dword v15, v16, s[12:13] sc1
	s_waitcnt lgkmcnt(0)
	global_load_dword v0, v16, s[16:17] sc1
	global_load_dword v1, v16, s[18:19] sc1
	global_load_dword v2, v16, s[20:21] sc1
	global_load_dword v3, v16, s[22:23] sc1
	global_load_dword v4, v16, s[24:25] sc1
	global_load_dword v5, v16, s[26:27] sc1
	global_load_dword v6, v16, s[30:31] sc1
	global_load_dword v7, v16, s[34:35] sc1
	global_load_dword v8, v16, s[36:37] sc1
	global_load_dword v9, v16, s[38:39] sc1
	global_load_dword v10, v16, s[40:41] sc1
	global_load_dword v11, v16, s[42:43] sc1
	global_load_dword v12, v16, s[44:45] sc1
	global_load_dword v13, v16, s[46:47] sc1
	global_load_dword v14, v16, s[48:49] sc1
	s_mov_b64 s[50:51], -1
	s_mov_b64 s[52:53], -1
	s_waitcnt vmcnt(14)
	v_add_u32_e32 v17, v0, v15
	s_waitcnt vmcnt(13)
	v_add_u32_e32 v17, v17, v1
	s_waitcnt vmcnt(12)
	v_add_u32_e32 v17, v17, v2
	s_waitcnt vmcnt(11)
	v_add_u32_e32 v17, v17, v3
	s_waitcnt vmcnt(10)
	v_add_u32_e32 v17, v17, v4
	s_waitcnt vmcnt(9)
	v_add_u32_e32 v17, v17, v5
	s_waitcnt vmcnt(8)
	v_add_u32_e32 v17, v17, v6
	s_waitcnt vmcnt(7)
	v_add_u32_e32 v17, v17, v7
	s_waitcnt vmcnt(6)
	v_add_u32_e32 v17, v17, v8
	s_waitcnt vmcnt(5)
	v_add_u32_e32 v17, v17, v9
	s_waitcnt vmcnt(4)
	v_add_u32_e32 v17, v17, v10
	s_waitcnt vmcnt(3)
	v_add_u32_e32 v17, v17, v11
	s_waitcnt vmcnt(2)
	v_add_u32_e32 v17, v17, v12
	s_waitcnt vmcnt(1)
	v_add_u32_e32 v17, v17, v13
	s_waitcnt vmcnt(0)
	v_add_u32_e32 v17, v17, v14
	v_cmp_eq_u32_e32 vcc, s0, v17
	s_cbranch_vccnz .LBB0_1011
	s_and_b32 s2, s1, 0xff
	s_cmp_eq_u32 s2, 0
	s_mov_b64 s[54:55], -1
	s_nop 0
	s_cbranch_scc0 .LBB0_1016
	global_load_dword v17, v16, s[8:9] sc1
	s_waitcnt vmcnt(0)
	v_cmp_eq_u32_e32 vcc, 0, v17
	s_cbranch_vccnz .LBB0_1018
	s_mov_b64 s[54:55], 0

; __device__ __forceinline__ unsigned xb_ld(unsigned* p)              { return __hip_atomic_load(p, __ATOMIC_RELAXED, __HIP_MEMORY_SCOPE_AGENT); }
; __device__ __forceinline__ unsigned xb_add(unsigned* p, unsigned v) { return __hip_atomic_fetch_add(p, v, __ATOMIC_RELAXED, __HIP_MEMORY_SCOPE_AGENT); }
; #define XB_SPIN(cond, bar) do { unsigned _sp = 0; while (cond) { __builtin_amdgcn_s_sleep(1); \
;     if ((++_sp & 255u) == 0u) { if (xb_ld(&(bar)[XB_TMO])) break; if (_sp > XB_SPIN_CAP) { atomicAdd(&(bar)[XB_TMO], 1u); break; } } } } while (0)
; __device__ __forceinline__ void xcd_barrier(const XcdBarrier& b) {
;     ...
;     const unsigned old = xb_add(&bar[XB_XSUB(b.x)], 1u);
;     const unsigned gen = old / nloc;
;     if (old + 1u == (gen + 1u) * nloc) {
;       __builtin_amdgcn_fence(__ATOMIC_RELEASE, "agent");
;       asm volatile("s_waitcnt vmcnt(0)" ::: "memory");
;       const unsigned og = xb_add(&bar[XB_TOP], 1u);
;       const unsigned tg = og / nx;
;       if (og + 1u == (tg + 1u) * nx) xb_add(&bar[XB_TOPGEN], 1u);
;       else XB_SPIN(xb_ld(&bar[XB_TOPGEN]) == tg, bar);
;       __builtin_amdgcn_fence(__ATOMIC_ACQUIRE, "agent");
;       xb_add(&bar[XB_XGEN(b.x)], 1u);
;       asm volatile("s_waitcnt vmcnt(0)" ::: "memory");
;     } else {
;       XB_SPIN(xb_ld(&bar[XB_XGEN(b.x)]) == gen, bar);
;       __builtin_amdgcn_fence(__ATOMIC_ACQUIRE, "agent");
;       asm volatile("s_waitcnt vmcnt(0)" ::: "memory");
;     }
.LBB0_1030:
	s_and_b32 s1, s0, 0xff
	s_mov_b64 s[26:27], -1
	s_cmp_lg_u32 s1, 0
	s_mov_b64 s[34:35], -1
	s_nop 0
	s_cbranch_scc1 .LBB0_1033
	global_load_dword v2, v0, s[18:19] sc1
	s_waitcnt vmcnt(0)
	v_cmp_eq_u32_e32 vcc, 0, v2
	s_cbranch_vccnz .LBB0_1035
	s_mov_b64 s[34:35], 0
	s_mov_b64 s[30:31], -1

; __device__ __forceinline__ unsigned xb_ld(unsigned* p)              { return __hip_atomic_load(p, __ATOMIC_RELAXED, __HIP_MEMORY_SCOPE_AGENT); }
; __device__ __forceinline__ unsigned xb_add(unsigned* p, unsigned v) { return __hip_atomic_fetch_add(p, v, __ATOMIC_RELAXED, __HIP_MEMORY_SCOPE_AGENT); }
; #define XB_SPIN(cond, bar) do { unsigned _sp = 0; while (cond) { __builtin_amdgcn_s_sleep(1); \
;     if ((++_sp & 255u) == 0u) { if (xb_ld(&(bar)[XB_TMO])) break; if (_sp > XB_SPIN_CAP) { atomicAdd(&(bar)[XB_TMO], 1u); break; } } } } while (0)
; __device__ __forceinline__ void xcd_barrier(const XcdBarrier& b) {
;     ...
;     const unsigned old = xb_add(&bar[XB_XSUB(b.x)], 1u);
;     const unsigned gen = old / nloc;
;     if (old + 1u == (gen + 1u) * nloc) {
;       __builtin_amdgcn_fence(__ATOMIC_RELEASE, "agent");
;       asm volatile("s_waitcnt vmcnt(0)" ::: "memory");
;       const unsigned og = xb_add(&bar[XB_TOP], 1u);
;       const unsigned tg = og / nx;
;       if (og + 1u == (tg + 1u) * nx) xb_add(&bar[XB_TOPGEN], 1u);
;       else XB_SPIN(xb_ld(&bar[XB_TOPGEN]) == tg, bar);
;       __builtin_amdgcn_fence(__ATOMIC_ACQUIRE, "agent");
;       xb_add(&bar[XB_XGEN(b.x)], 1u);
;       asm volatile("s_waitcnt vmcnt(0)" ::: "memory");
;     } else {
;       XB_SPIN(xb_ld(&bar[XB_XGEN(b.x)]) == gen, bar);
;       __builtin_amdgcn_fence(__ATOMIC_ACQUIRE, "agent");
;       asm volatile("s_waitcnt vmcnt(0)" ::: "memory");
;     }
.LBB0_1047:
	s_and_b32 s1, s0, 0xff
	s_cmp_lg_u32 s1, 0
	s_mov_b64 s[30:31], -1
	s_nop 0
	s_cbranch_scc1 .LBB0_1050
	global_load_dword v1, v0, s[18:19] sc1
	s_waitcnt vmcnt(0)
	v_cmp_eq_u32_e32 vcc, 0, v1
	s_cbranch_vccnz .LBB0_1052
	s_mov_b64 s[30:31], 0
	s_mov_b64 s[26:27], -1

; __device__ __forceinline__ unsigned xb_ld(unsigned* p)              { return __hip_atomic_load(p, __ATOMIC_RELAXED, __HIP_MEMORY_SCOPE_AGENT); }
; __device__ __forceinline__ void xcd_barrier_complete(unsigned* bar, unsigned x, unsigned& nloc, unsigned& nx) {
;   const unsigned G = gridDim.x * gridDim.y * gridDim.z;
;   unsigned sum, cnt, mine, sp = 0u;
;   for (;;) {
;     sum = 0u; cnt = 0u; mine = 0u;
; #pragma unroll
;     for (unsigned j = 0; j < 16; ++j) { const unsigned c = xb_ld(&bar[XB_XCNT(j)]); sum += c; cnt += (c > 0u) ? 1u : 0u; mine = (j == x) ? c : mine; }
;     if (sum == G) break;
;     __builtin_amdgcn_s_sleep(1);
;     if ((++sp & 255u) == 0u) { if (xb_ld(&bar[XB_TMO])) break; if (sp > XB_SPIN_CAP) { atomicAdd(&bar[XB_TMO], 1u); break; } }
;   }
;   nloc = mine > 0u ? mine : 1u; nx = cnt > 0u ? cnt : 1u;
; }
.LBB0_1069:
	global_load_dword v15, v16, s[10:11] sc1
	s_waitcnt lgkmcnt(0)
	global_load_dword v0, v16, s[12:13] sc1
	global_load_dword v1, v16, s[16:17] sc1
	global_load_dword v2, v16, s[18:19] sc1
	global_load_dword v3, v16, s[20:21] sc1
	global_load_dword v4, v16, s[22:23] sc1
	global_load_dword v5, v16, s[24:25] sc1
	global_load_dword v6, v16, s[26:27] sc1
	global_load_dword v7, v16, s[30:31] sc1
	global_load_dword v8, v16, s[34:35] sc1
	global_load_dword v9, v16, s[36:37] sc1
	global_load_dword v10, v16, s[38:39] sc1
	global_load_dword v11, v16, s[40:41] sc1
	global_load_dword v12, v16, s[42:43] sc1
	global_load_dword v13, v16, s[44:45] sc1
	global_load_dword v14, v16, s[46:47] sc1
	s_mov_b64 s[48:49], -1
	s_mov_b64 s[50:51], -1
	s_waitcnt vmcnt(14)
	v_add_u32_e32 v17, v0, v15
	s_waitcnt vmcnt(13)
	v_add_u32_e32 v17, v17, v1
	s_waitcnt vmcnt(12)
	v_add_u32_e32 v17, v17, v2
	s_waitcnt vmcnt(11)
	v_add_u32_e32 v17, v17, v3
	s_waitcnt vmcnt(10)
	v_add_u32_e32 v17, v17, v4
	s_waitcnt vmcnt(9)
	v_add_u32_e32 v17, v17, v5
	s_waitcnt vmcnt(8)
	v_add_u32_e32 v17, v17, v6
	s_waitcnt vmcnt(7)
	v_add_u32_e32 v17, v17, v7
	s_waitcnt vmcnt(6)
	v_add_u32_e32 v17, v17, v8
	s_waitcnt vmcnt(5)
	v_add_u32_e32 v17, v17, v9
	s_waitcnt vmcnt(4)
	v_add_u32_e32 v17, v17, v10
	s_waitcnt vmcnt(3)
	v_add_u32_e32 v17, v17, v11
	s_waitcnt vmcnt(2)
	v_add_u32_e32 v17, v17, v12
	s_waitcnt vmcnt(1)
	v_add_u32_e32 v17, v17, v13
	s_waitcnt vmcnt(0)
	v_add_u32_e32 v17, v17, v14
	v_cmp_eq_u32_e32 vcc, s0, v17
	s_cbranch_vccnz .LBB0_1068
	s_and_b32 s2, s1, 0xff
	s_cmp_eq_u32 s2, 0
	s_mov_b64 s[52:53], -1
	s_nop 0
	s_cbranch_scc0 .LBB0_1073
	global_load_dword v17, v16, s[8:9] sc1
	s_waitcnt vmcnt(0)
	v_cmp_eq_u32_e32 vcc, 0, v17
	s_cbranch_vccnz .LBB0_1075
	s_mov_b64 s[52:53], 0

; __device__ __forceinline__ unsigned xb_ld(unsigned* p)              { return __hip_atomic_load(p, __ATOMIC_RELAXED, __HIP_MEMORY_SCOPE_AGENT); }
; __device__ __forceinline__ unsigned xb_add(unsigned* p, unsigned v) { return __hip_atomic_fetch_add(p, v, __ATOMIC_RELAXED, __HIP_MEMORY_SCOPE_AGENT); }
; #define XB_SPIN(cond, bar) do { unsigned _sp = 0; while (cond) { __builtin_amdgcn_s_sleep(1); \
;     if ((++_sp & 255u) == 0u) { if (xb_ld(&(bar)[XB_TMO])) break; if (_sp > XB_SPIN_CAP) { atomicAdd(&(bar)[XB_TMO], 1u); break; } } } } while (0)
; __device__ __forceinline__ void xcd_barrier(const XcdBarrier& b) {
;     ...
;     const unsigned old = xb_add(&bar[XB_XSUB(b.x)], 1u);
;     const unsigned gen = old / nloc;
;     if (old + 1u == (gen + 1u) * nloc) {
;       __builtin_amdgcn_fence(__ATOMIC_RELEASE, "agent");
;       asm volatile("s_waitcnt vmcnt(0)" ::: "memory");
;       const unsigned og = xb_add(&bar[XB_TOP], 1u);
;       const unsigned tg = og / nx;
;       if (og + 1u == (tg + 1u) * nx) xb_add(&bar[XB_TOPGEN], 1u);
;       else XB_SPIN(xb_ld(&bar[XB_TOPGEN]) == tg, bar);
;       __builtin_amdgcn_fence(__ATOMIC_ACQUIRE, "agent");
;       xb_add(&bar[XB_XGEN(b.x)], 1u);
;       asm volatile("s_waitcnt vmcnt(0)" ::: "memory");
;     } else {
;       XB_SPIN(xb_ld(&bar[XB_XGEN(b.x)]) == gen, bar);
;       __builtin_amdgcn_fence(__ATOMIC_ACQUIRE, "agent");
;       asm volatile("s_waitcnt vmcnt(0)" ::: "memory");
;     }
.LBB0_1087:
	s_and_b32 s1, s0, 0xff
	s_mov_b64 s[24:25], -1
	s_cmp_lg_u32 s1, 0
	s_mov_b64 s[30:31], -1
	s_nop 0
	s_cbranch_scc1 .LBB0_1090
	global_load_dword v2, v0, s[16:17] sc1
	s_waitcnt vmcnt(0)
	v_cmp_eq_u32_e32 vcc, 0, v2
	s_cbranch_vccnz .LBB0_1092
	s_mov_b64 s[30:31], 0
	s_mov_b64 s[26:27], -1

; __device__ __forceinline__ unsigned xb_ld(unsigned* p)              { return __hip_atomic_load(p, __ATOMIC_RELAXED, __HIP_MEMORY_SCOPE_AGENT); }
; __device__ __forceinline__ unsigned xb_add(unsigned* p, unsigned v) { return __hip_atomic_fetch_add(p, v, __ATOMIC_RELAXED, __HIP_MEMORY_SCOPE_AGENT); }
; #define XB_SPIN(cond, bar) do { unsigned _sp = 0; while (cond) { __builtin_amdgcn_s_sleep(1); \
;     if ((++_sp & 255u) == 0u) { if (xb_ld(&(bar)[XB_TMO])) break; if (_sp > XB_SPIN_CAP) { atomicAdd(&(bar)[XB_TMO], 1u); break; } } } } while (0)
; __device__ __forceinline__ void xcd_barrier(const XcdBarrier& b) {
;     ...
;     const unsigned old = xb_add(&bar[XB_XSUB(b.x)], 1u);
;     const unsigned gen = old / nloc;
;     if (old + 1u == (gen + 1u) * nloc) {
;       __builtin_amdgcn_fence(__ATOMIC_RELEASE, "agent");
;       asm volatile("s_waitcnt vmcnt(0)" ::: "memory");
;       const unsigned og = xb_add(&bar[XB_TOP], 1u);
;       const unsigned tg = og / nx;
;       if (og + 1u == (tg + 1u) * nx) xb_add(&bar[XB_TOPGEN], 1u);
;       else XB_SPIN(xb_ld(&bar[XB_TOPGEN]) == tg, bar);
;       __builtin_amdgcn_fence(__ATOMIC_ACQUIRE, "agent");
;       xb_add(&bar[XB_XGEN(b.x)], 1u);
;       asm volatile("s_waitcnt vmcnt(0)" ::: "memory");
;     } else {
;       XB_SPIN(xb_ld(&bar[XB_XGEN(b.x)]) == gen, bar);
;       __builtin_amdgcn_fence(__ATOMIC_ACQUIRE, "agent");
;       asm volatile("s_waitcnt vmcnt(0)" ::: "memory");
;     }
.LBB0_1104:
	s_and_b32 s1, s0, 0xff
	s_cmp_lg_u32 s1, 0
	s_mov_b64 s[26:27], -1
	s_nop 0
	s_cbranch_scc1 .LBB0_1107
	global_load_dword v1, v0, s[16:17] sc1
	s_waitcnt vmcnt(0)
	v_cmp_eq_u32_e32 vcc, 0, v1
	s_cbranch_vccnz .LBB0_1109
	s_mov_b64 s[26:27], 0
	s_mov_b64 s[24:25], -1

; __device__ __forceinline__ unsigned xb_ld(unsigned* p)              { return __hip_atomic_load(p, __ATOMIC_RELAXED, __HIP_MEMORY_SCOPE_AGENT); }
; __device__ __forceinline__ void xcd_barrier_complete(unsigned* bar, unsigned x, unsigned& nloc, unsigned& nx) {
;   const unsigned G = gridDim.x * gridDim.y * gridDim.z;
;   unsigned sum, cnt, mine, sp = 0u;
;   for (;;) {
;     sum = 0u; cnt = 0u; mine = 0u;
; #pragma unroll
;     for (unsigned j = 0; j < 16; ++j) { const unsigned c = xb_ld(&bar[XB_XCNT(j)]); sum += c; cnt += (c > 0u) ? 1u : 0u; mine = (j == x) ? c : mine; }
;     if (sum == G) break;
;     __builtin_amdgcn_s_sleep(1);
;     if ((++sp & 255u) == 0u) { if (xb_ld(&bar[XB_TMO])) break; if (sp > XB_SPIN_CAP) { atomicAdd(&bar[XB_TMO], 1u); break; } }
;   }
;   nloc = mine > 0u ? mine : 1u; nx = cnt > 0u ? cnt : 1u;
; }
.LBB0_1341:
	global_load_dword v15, v16, s[10:11] sc1
	s_waitcnt lgkmcnt(0)
	global_load_dword v0, v16, s[12:13] sc1
	global_load_dword v1, v16, s[14:15] sc1
	global_load_dword v2, v16, s[16:17] sc1
	global_load_dword v3, v16, s[18:19] sc1
	global_load_dword v4, v16, s[20:21] sc1
	global_load_dword v5, v16, s[22:23] sc1
	global_load_dword v6, v16, s[24:25] sc1
	global_load_dword v7, v16, s[26:27] sc1
	global_load_dword v8, v16, s[30:31] sc1
	global_load_dword v9, v16, s[34:35] sc1
	global_load_dword v10, v16, s[36:37] sc1
	global_load_dword v11, v16, s[38:39] sc1
	global_load_dword v12, v16, s[40:41] sc1
	global_load_dword v13, v16, s[42:43] sc1
	global_load_dword v14, v16, s[44:45] sc1
	s_mov_b64 s[46:47], -1
	s_mov_b64 s[48:49], -1
	s_waitcnt vmcnt(14)
	v_add_u32_e32 v17, v0, v15
	s_waitcnt vmcnt(13)
	v_add_u32_e32 v17, v17, v1
	s_waitcnt vmcnt(12)
	v_add_u32_e32 v17, v17, v2
	s_waitcnt vmcnt(11)
	v_add_u32_e32 v17, v17, v3
	s_waitcnt vmcnt(10)
	v_add_u32_e32 v17, v17, v4
	s_waitcnt vmcnt(9)
	v_add_u32_e32 v17, v17, v5
	s_waitcnt vmcnt(8)
	v_add_u32_e32 v17, v17, v6
	s_waitcnt vmcnt(7)
	v_add_u32_e32 v17, v17, v7
	s_waitcnt vmcnt(6)
	v_add_u32_e32 v17, v17, v8
	s_waitcnt vmcnt(5)
	v_add_u32_e32 v17, v17, v9
	s_waitcnt vmcnt(4)
	v_add_u32_e32 v17, v17, v10
	s_waitcnt vmcnt(3)
	v_add_u32_e32 v17, v17, v11
	s_waitcnt vmcnt(2)
	v_add_u32_e32 v17, v17, v12
	s_waitcnt vmcnt(1)
	v_add_u32_e32 v17, v17, v13
	s_waitcnt vmcnt(0)
	v_add_u32_e32 v17, v17, v14
	v_cmp_eq_u32_e32 vcc, s0, v17
	s_cbranch_vccnz .LBB0_1340
	s_and_b32 s2, s1, 0xff
	s_cmp_eq_u32 s2, 0
	s_mov_b64 s[50:51], -1
	s_nop 0
	s_cbranch_scc0 .LBB0_1345
	global_load_dword v17, v16, s[8:9] sc1
	s_waitcnt vmcnt(0)
	v_cmp_eq_u32_e32 vcc, 0, v17
	s_cbranch_vccnz .LBB0_1347
	s_mov_b64 s[50:51], 0

; __device__ __forceinline__ unsigned xb_ld(unsigned* p)              { return __hip_atomic_load(p, __ATOMIC_RELAXED, __HIP_MEMORY_SCOPE_AGENT); }
; __device__ __forceinline__ unsigned xb_add(unsigned* p, unsigned v) { return __hip_atomic_fetch_add(p, v, __ATOMIC_RELAXED, __HIP_MEMORY_SCOPE_AGENT); }
; #define XB_SPIN(cond, bar) do { unsigned _sp = 0; while (cond) { __builtin_amdgcn_s_sleep(1); \
;     if ((++_sp & 255u) == 0u) { if (xb_ld(&(bar)[XB_TMO])) break; if (_sp > XB_SPIN_CAP) { atomicAdd(&(bar)[XB_TMO], 1u); break; } } } } while (0)
; __device__ __forceinline__ void xcd_barrier(const XcdBarrier& b) {
;     ...
;     const unsigned old = xb_add(&bar[XB_XSUB(b.x)], 1u);
;     const unsigned gen = old / nloc;
;     if (old + 1u == (gen + 1u) * nloc) {
;       __builtin_amdgcn_fence(__ATOMIC_RELEASE, "agent");
;       asm volatile("s_waitcnt vmcnt(0)" ::: "memory");
;       const unsigned og = xb_add(&bar[XB_TOP], 1u);
;       const unsigned tg = og / nx;
;       if (og + 1u == (tg + 1u) * nx) xb_add(&bar[XB_TOPGEN], 1u);
;       else XB_SPIN(xb_ld(&bar[XB_TOPGEN]) == tg, bar);
;       __builtin_amdgcn_fence(__ATOMIC_ACQUIRE, "agent");
;       xb_add(&bar[XB_XGEN(b.x)], 1u);
;       asm volatile("s_waitcnt vmcnt(0)" ::: "memory");
;     } else {
;       XB_SPIN(xb_ld(&bar[XB_XGEN(b.x)]) == gen, bar);
;       __builtin_amdgcn_fence(__ATOMIC_ACQUIRE, "agent");
;       asm volatile("s_waitcnt vmcnt(0)" ::: "memory");
;     }
.LBB0_1359:
	s_and_b32 s1, s0, 0xff
	s_mov_b64 s[22:23], -1
	s_cmp_lg_u32 s1, 0
	s_mov_b64 s[26:27], -1
	s_nop 0
	s_cbranch_scc1 .LBB0_1362
	global_load_dword v2, v0, s[14:15] sc1
	s_waitcnt vmcnt(0)
	v_cmp_eq_u32_e32 vcc, 0, v2
	s_cbranch_vccnz .LBB0_1364
	s_mov_b64 s[26:27], 0
	s_mov_b64 s[24:25], -1

; __device__ __forceinline__ unsigned xb_ld(unsigned* p)              { return __hip_atomic_load(p, __ATOMIC_RELAXED, __HIP_MEMORY_SCOPE_AGENT); }
; __device__ __forceinline__ unsigned xb_add(unsigned* p, unsigned v) { return __hip_atomic_fetch_add(p, v, __ATOMIC_RELAXED, __HIP_MEMORY_SCOPE_AGENT); }
; #define XB_SPIN(cond, bar) do { unsigned _sp = 0; while (cond) { __builtin_amdgcn_s_sleep(1); \
;     if ((++_sp & 255u) == 0u) { if (xb_ld(&(bar)[XB_TMO])) break; if (_sp > XB_SPIN_CAP) { atomicAdd(&(bar)[XB_TMO], 1u); break; } } } } while (0)
; __device__ __forceinline__ void xcd_barrier(const XcdBarrier& b) {
;     ...
;     const unsigned old = xb_add(&bar[XB_XSUB(b.x)], 1u);
;     const unsigned gen = old / nloc;
;     if (old + 1u == (gen + 1u) * nloc) {
;       __builtin_amdgcn_fence(__ATOMIC_RELEASE, "agent");
;       asm volatile("s_waitcnt vmcnt(0)" ::: "memory");
;       const unsigned og = xb_add(&bar[XB_TOP], 1u);
;       const unsigned tg = og / nx;
;       if (og + 1u == (tg + 1u) * nx) xb_add(&bar[XB_TOPGEN], 1u);
;       else XB_SPIN(xb_ld(&bar[XB_TOPGEN]) == tg, bar);
;       __builtin_amdgcn_fence(__ATOMIC_ACQUIRE, "agent");
;       xb_add(&bar[XB_XGEN(b.x)], 1u);
;       asm volatile("s_waitcnt vmcnt(0)" ::: "memory");
;     } else {
;       XB_SPIN(xb_ld(&bar[XB_XGEN(b.x)]) == gen, bar);
;       __builtin_amdgcn_fence(__ATOMIC_ACQUIRE, "agent");
;       asm volatile("s_waitcnt vmcnt(0)" ::: "memory");
;     }
.LBB0_1376:
	s_and_b32 s1, s0, 0xff
	s_cmp_lg_u32 s1, 0
	s_mov_b64 s[24:25], -1
	s_nop 0
	s_cbranch_scc1 .LBB0_1379
	global_load_dword v1, v0, s[14:15] sc1
	s_waitcnt vmcnt(0)
	v_cmp_eq_u32_e32 vcc, 0, v1
	s_cbranch_vccnz .LBB0_1381
	s_mov_b64 s[24:25], 0
	s_mov_b64 s[22:23], -1

; __device__ __forceinline__ unsigned xb_ld(unsigned* p)              { return __hip_atomic_load(p, __ATOMIC_RELAXED, __HIP_MEMORY_SCOPE_AGENT); }
; __device__ __forceinline__ void xcd_barrier_complete(unsigned* bar, unsigned x, unsigned& nloc, unsigned& nx) {
;   const unsigned G = gridDim.x * gridDim.y * gridDim.z;
;   unsigned sum, cnt, mine, sp = 0u;
;   for (;;) {
;     sum = 0u; cnt = 0u; mine = 0u;
; #pragma unroll
;     for (unsigned j = 0; j < 16; ++j) { const unsigned c = xb_ld(&bar[XB_XCNT(j)]); sum += c; cnt += (c > 0u) ? 1u : 0u; mine = (j == x) ? c : mine; }
;     if (sum == G) break;
;     __builtin_amdgcn_s_sleep(1);
;     if ((++sp & 255u) == 0u) { if (xb_ld(&bar[XB_TMO])) break; if (sp > XB_SPIN_CAP) { atomicAdd(&bar[XB_TMO], 1u); break; } }
;   }
;   nloc = mine > 0u ? mine : 1u; nx = cnt > 0u ? cnt : 1u;
; }
.LBB0_1692:
	global_load_dword v15, v16, s[6:7] sc1
	s_waitcnt lgkmcnt(0)
	global_load_dword v0, v16, s[8:9] sc1
	global_load_dword v1, v16, s[10:11] sc1
	global_load_dword v2, v16, s[12:13] sc1
	global_load_dword v3, v16, s[14:15] sc1
	global_load_dword v4, v16, s[16:17] sc1
	global_load_dword v5, v16, s[18:19] sc1
	global_load_dword v6, v16, s[20:21] sc1
	global_load_dword v7, v16, s[22:23] sc1
	global_load_dword v8, v16, s[24:25] sc1
	global_load_dword v9, v16, s[26:27] sc1
	global_load_dword v10, v16, s[30:31] sc1
	global_load_dword v11, v16, s[34:35] sc1
	global_load_dword v12, v16, s[36:37] sc1
	global_load_dword v13, v16, s[38:39] sc1
	global_load_dword v14, v16, s[40:41] sc1
	s_mov_b64 s[42:43], -1
	s_mov_b64 s[44:45], -1
	s_waitcnt vmcnt(14)
	v_add_u32_e32 v17, v0, v15
	s_waitcnt vmcnt(13)
	v_add_u32_e32 v17, v17, v1
	s_waitcnt vmcnt(12)
	v_add_u32_e32 v17, v17, v2
	s_waitcnt vmcnt(11)
	v_add_u32_e32 v17, v17, v3
	s_waitcnt vmcnt(10)
	v_add_u32_e32 v17, v17, v4
	s_waitcnt vmcnt(9)
	v_add_u32_e32 v17, v17, v5
	s_waitcnt vmcnt(8)
	v_add_u32_e32 v17, v17, v6
	s_waitcnt vmcnt(7)
	v_add_u32_e32 v17, v17, v7
	s_waitcnt vmcnt(6)
	v_add_u32_e32 v17, v17, v8
	s_waitcnt vmcnt(5)
	v_add_u32_e32 v17, v17, v9
	s_waitcnt vmcnt(4)
	v_add_u32_e32 v17, v17, v10
	s_waitcnt vmcnt(3)
	v_add_u32_e32 v17, v17, v11
	s_waitcnt vmcnt(2)
	v_add_u32_e32 v17, v17, v12
	s_waitcnt vmcnt(1)
	v_add_u32_e32 v17, v17, v13
	s_waitcnt vmcnt(0)
	v_add_u32_e32 v17, v17, v14
	v_cmp_eq_u32_e32 vcc, s0, v17
	s_cbranch_vccnz .LBB0_1691
	s_and_b32 s33, s1, 0xff
	s_cmp_eq_u32 s33, 0
	s_mov_b64 s[46:47], -1
	s_nop 0
	s_cbranch_scc0 .LBB0_1696
	global_load_dword v17, v16, s[4:5] sc1
	s_waitcnt vmcnt(0)
	v_cmp_eq_u32_e32 vcc, 0, v17
	s_cbranch_vccnz .LBB0_1698
	s_mov_b64 s[46:47], 0

; __device__ __forceinline__ unsigned xb_ld(unsigned* p)              { return __hip_atomic_load(p, __ATOMIC_RELAXED, __HIP_MEMORY_SCOPE_AGENT); }
; __device__ __forceinline__ unsigned xb_add(unsigned* p, unsigned v) { return __hip_atomic_fetch_add(p, v, __ATOMIC_RELAXED, __HIP_MEMORY_SCOPE_AGENT); }
; #define XB_SPIN(cond, bar) do { unsigned _sp = 0; while (cond) { __builtin_amdgcn_s_sleep(1); \
;     if ((++_sp & 255u) == 0u) { if (xb_ld(&(bar)[XB_TMO])) break; if (_sp > XB_SPIN_CAP) { atomicAdd(&(bar)[XB_TMO], 1u); break; } } } } while (0)
; __device__ __forceinline__ void xcd_barrier(const XcdBarrier& b) {
;     ...
;     const unsigned old = xb_add(&bar[XB_XSUB(b.x)], 1u);
;     const unsigned gen = old / nloc;
;     if (old + 1u == (gen + 1u) * nloc) {
;       __builtin_amdgcn_fence(__ATOMIC_RELEASE, "agent");
;       asm volatile("s_waitcnt vmcnt(0)" ::: "memory");
;       const unsigned og = xb_add(&bar[XB_TOP], 1u);
;       const unsigned tg = og / nx;
;       if (og + 1u == (tg + 1u) * nx) xb_add(&bar[XB_TOPGEN], 1u);
;       else XB_SPIN(xb_ld(&bar[XB_TOPGEN]) == tg, bar);
;       __builtin_amdgcn_fence(__ATOMIC_ACQUIRE, "agent");
;       xb_add(&bar[XB_XGEN(b.x)], 1u);
;       asm volatile("s_waitcnt vmcnt(0)" ::: "memory");
;     } else {
;       XB_SPIN(xb_ld(&bar[XB_XGEN(b.x)]) == gen, bar);
;       __builtin_amdgcn_fence(__ATOMIC_ACQUIRE, "agent");
;       asm volatile("s_waitcnt vmcnt(0)" ::: "memory");
;     }
.LBB0_1710:
	s_and_b32 s1, s0, 0xff
	s_mov_b64 s[18:19], -1
	s_cmp_lg_u32 s1, 0
	s_mov_b64 s[22:23], -1
	s_nop 0
	s_cbranch_scc1 .LBB0_1713
	global_load_dword v2, v0, s[10:11] sc1
	s_waitcnt vmcnt(0)
	v_cmp_eq_u32_e32 vcc, 0, v2
	s_cbranch_vccnz .LBB0_1715
	s_mov_b64 s[22:23], 0
	s_mov_b64 s[20:21], -1

; __device__ __forceinline__ unsigned xb_ld(unsigned* p)              { return __hip_atomic_load(p, __ATOMIC_RELAXED, __HIP_MEMORY_SCOPE_AGENT); }
; __device__ __forceinline__ unsigned xb_add(unsigned* p, unsigned v) { return __hip_atomic_fetch_add(p, v, __ATOMIC_RELAXED, __HIP_MEMORY_SCOPE_AGENT); }
; #define XB_SPIN(cond, bar) do { unsigned _sp = 0; while (cond) { __builtin_amdgcn_s_sleep(1); \
;     if ((++_sp & 255u) == 0u) { if (xb_ld(&(bar)[XB_TMO])) break; if (_sp > XB_SPIN_CAP) { atomicAdd(&(bar)[XB_TMO], 1u); break; } } } } while (0)
; __device__ __forceinline__ void xcd_barrier(const XcdBarrier& b) {
;     ...
;     const unsigned old = xb_add(&bar[XB_XSUB(b.x)], 1u);
;     const unsigned gen = old / nloc;
;     if (old + 1u == (gen + 1u) * nloc) {
;       __builtin_amdgcn_fence(__ATOMIC_RELEASE, "agent");
;       asm volatile("s_waitcnt vmcnt(0)" ::: "memory");
;       const unsigned og = xb_add(&bar[XB_TOP], 1u);
;       const unsigned tg = og / nx;
;       if (og + 1u == (tg + 1u) * nx) xb_add(&bar[XB_TOPGEN], 1u);
;       else XB_SPIN(xb_ld(&bar[XB_TOPGEN]) == tg, bar);
;       __builtin_amdgcn_fence(__ATOMIC_ACQUIRE, "agent");
;       xb_add(&bar[XB_XGEN(b.x)], 1u);
;       asm volatile("s_waitcnt vmcnt(0)" ::: "memory");
;     } else {
;       XB_SPIN(xb_ld(&bar[XB_XGEN(b.x)]) == gen, bar);
;       __builtin_amdgcn_fence(__ATOMIC_ACQUIRE, "agent");
;       asm volatile("s_waitcnt vmcnt(0)" ::: "memory");
;     }
.LBB0_1727:
	s_and_b32 s1, s0, 0xff
	s_cmp_lg_u32 s1, 0
	s_mov_b64 s[20:21], -1
	s_nop 0
	s_cbranch_scc1 .LBB0_1730
	global_load_dword v1, v0, s[10:11] sc1
	s_waitcnt vmcnt(0)
	v_cmp_eq_u32_e32 vcc, 0, v1
	s_cbranch_vccnz .LBB0_1732
	s_mov_b64 s[20:21], 0
	s_mov_b64 s[18:19], -1
